# scan: stage writes spread under the output MFMAs, score tile X unconditional (counted wait instead of a full drain)
# speedup vs baseline: 1.0054x; 1.0054x over previous
; #define LAS __attribute__((address_space(3)))
; __device__ void scan_phase(LAS unsigned char* lds, const Params& p) {
;     const int tid = threadIdx.x, w = __builtin_amdgcn_readfirstlane(tid >> 6), lane = tid & 63, ln = lane & 15, lq = lane >> 4;
;     constexpr int QST = 136, VST = 36;
;     constexpr int OFF_KS = 17408, OFF_V = 34816, BUFB = 39424;
;     LAS bf16_t* Sr = (LAS bf16_t*)(lds + 2 * BUFB);
;     LAS float* scs = (LAS float*)(lds + 2 * BUFB + 9216);
;     bf16_t* O = (bf16_t*)p.out;
;     bf16_t* Odummy = (bf16_t*)(p.ws + WS_A) + (size_t)blockIdx.x * 64 * 512;
;     const float* RT = (const float*)(p.ws + WS_RT);
;     const int eb = w & 1, tb = w >> 1;
;     if (w >= 4) __builtin_amdgcn_s_setprio(1);
;     for (int item = blockIdx.x; item < 256; item += gridDim.x) {
;         const int seq = (item & 7) + 8 * (item >> 5), es = (item >> 3) & 3;
;         const int dir = seq & 1, h = (seq >> 1) & 3, b = seq >> 3;
;         const char* Qx = (const char*)((const bf16_t*)(p.ws + (dir ? WS_QB : WS_QF)) + h * 128);
;         const char* Kx = (const char*)((const bf16_t*)(p.ws + (dir ? WS_KB : WS_KF)) + h * 128);
;         const char* Vx = (const char*)((const bf16_t*)(p.ws + WS_V) + h * 128 + es * 32);
;         const char* Rx = (const char*)(RT + (size_t)dir * NCHUNK * 512 + h * 128);
;         const char* Tx = (const char*)(RT + (size_t)(2 + dir) * NCHUNK * 512 + h * 128);
;         const unsigned qoff0 = (unsigned)((dir ? 63 - (tid >> 4) : (tid >> 4)) * 1024 + (tid & 15) * 16), qstep = dir ? (unsigned)-32768 : 32768u;
;         const unsigned voff = (unsigned)((dir ? 63 - (tid >> 3) : (tid >> 3)) * 1024 + (tid & 7) * 8), roff = (unsigned)(tid & 127) * 4u;
;         f32x4 S[2] = {(f32x4){0.f, 0.f, 0.f, 0.f}, (f32x4){0.f, 0.f, 0.f, 0.f}};
;         float tailp = 0.f;
;         u32x4 k4A[2], k4B[2], k4C[2], k4D[2]; u32x4 q4A[2], q4B[2], q4C[2], q4D[2]; u32x2 v4A, v4B, v4C, v4D; float rvA, tlA, rvB, tlB, rvC, tlC, rvD, tlD;
.LBB0_256:
	s_cmp_lt_i32 s72, 4
	s_cselect_b64 s[8:9], -1, 0
	s_waitcnt lgkmcnt(0)
	s_and_b64 s[38:39], s[8:9], s[6:7]
	s_andn2_b64 vcc, exec, s[38:39]
	s_cbranch_vccnz .LBB0_308
	v_lshrrev_b32_e32 v1, 6, v0
	s_nop 0
	v_readfirstlane_b32 s6, v1
	s_lshr_b32 s7, s6, 1
	s_and_b32 s8, s6, 1
	s_mov_b32 s9, s2
	s_load_dword s35, s[0:1], 0x98
	s_cmp_ge_u32 s7, 2
	s_cselect_b32 s11, 1, 0
	s_cmp_le_u32 s8, s7
	s_cselect_b32 s13, 1, 0
	s_add_u32 s3, s8, 2
	s_cmp_le_u32 s3, s7
	s_cselect_b32 s14, 1, 0
	v_and_b32_e32 v58, 15, v0
	v_bfe_u32 v59, v0, 4, 2
	v_lshrrev_b32_e32 v90, 2, v58
	v_and_b32_e32 v91, 3, v0
	v_and_b32_e32 v92, 63, v0
	v_lshlrev_b32_e32 v93, 2, v59
	v_add_u32_e32 v1, 0, v93
	v_cmp_le_u32_e64 s[94:95], v1, v58
	v_add_u32_e32 v1, 1, v93
	v_cmp_le_u32_e64 s[96:97], v1, v58
	v_add_u32_e32 v1, 2, v93
	v_cmp_le_u32_e64 s[98:99], v1, v58
	v_add_u32_e32 v1, 3, v93
	v_cmp_le_u32_e64 vcc, v1, v58
	s_cmp_eq_u32 s8, s7
	s_cselect_b64 s[76:77], s[94:95], -1
	s_cselect_b64 s[78:79], s[96:97], -1
	s_cselect_b64 s[80:81], s[98:99], -1
	s_cselect_b64 s[82:83], vcc, -1
	s_cmp_eq_u32 s13, 0
	s_cselect_b64 s[76:77], 0, s[76:77]
	s_cselect_b64 s[78:79], 0, s[78:79]
	s_cselect_b64 s[80:81], 0, s[80:81]
	s_cselect_b64 s[82:83], 0, s[82:83]
	s_add_u32 s3, s8, 2
	s_cmp_eq_u32 s3, s7
	s_cselect_b64 s[84:85], s[94:95], -1
	s_cselect_b64 s[88:89], s[96:97], -1
	s_cselect_b64 s[90:91], s[98:99], -1
	s_cselect_b64 s[92:93], vcc, -1
	v_lshrrev_b32_e32 v1, 4, v0
	v_mul_u32_u24_e32 v60, 272, v1
	v_lshl_add_u32 v60, v58, 4, v60
	v_lshrrev_b32_e32 v1, 3, v0
	v_mul_u32_u24_e32 v63, 72, v1
	v_and_b32_e32 v1, 7, v0
	v_lshl_add_u32 v63, v1, 3, v63
	v_and_b32_e32 v1, 0x7f, v0
	v_lshlrev_b32_e32 v56, 2, v1
	s_cmp_lt_u32 s6, 2
	s_mov_b32 s4, 127488
	s_cselect_b32 s3, s4, 129024
	v_add_u32_e32 v78, s3, v56
	s_lshl_b32 s3, s7, 7
	s_add_u32 s3, s3, 127488
	v_lshl_add_u32 v79, v58, 2, s3
	s_mul_i32 s3, s7, 2304
	s_lshl_b32 s4, s8, 5
	s_add_u32 s3, s3, s4
	v_mul_u32_u24_e32 v1, 72, v58
	v_lshl_add_u32 v1, v59, 3, v1
	v_add_u32_e32 v1, s3, v1
	v_add_u32_e32 v80, 118272, v1
	v_add_u32_e32 v81, 131088, v1
	s_mul_i32 s3, s8, 4352
	v_mul_u32_u24_e32 v69, 272, v58
	v_lshl_add_u32 v69, v59, 4, v69
	v_add_u32_e32 v69, s3, v69
	s_mul_i32 s3, s7, 4352
	v_mul_u32_u24_e32 v66, 272, v58
	v_lshl_add_u32 v66, v59, 4, v66
	v_add_u32_e32 v66, s3, v66
	s_lshl_b32 s3, s7, 11
	v_lshl_add_u32 v1, v92, 4, s3
	s_lshl_b32 s4, s8, 3
	v_add_u32_e32 v86, 140304, v1
	v_add_u32_e32 v84, s4, v86
	v_add_u32_e32 v87, 148496, v1
	v_add_u32_e32 v85, s4, v87
	v_lshl_add_u32 v1, v59, 3, v90
	v_mul_u32_u24_e32 v1, 72, v1
	v_lshl_add_u32 v1, v91, 3, v1
	s_lshl_b32 s4, s8, 5
	v_add_u32_e32 v1, s4, v1
	v_add_u32_e32 v82, 118272, v1
	v_add_u32_e32 v83, 131088, v1
	v_lshl_add_u32 v1, v59, 2, v90
	v_mul_u32_u24_e32 v72, 72, v1
	v_lshl_add_u32 v72, v91, 3, v72
	v_add_u32_e32 v72, s4, v72
	v_mul_u32_u24_e32 v75, 272, v1
	v_lshl_add_u32 v75, v91, 3, v75
	s_lshl_b32 s3, s7, 6
	v_add_u32_e32 v75, s3, v75
	v_add_u32_e32 v61, 39424, v60
	v_add_u32_e32 v62, 78848, v60
	v_add_u32_e32 v64, 39424, v63
	v_add_u32_e32 v65, 78848, v63
	v_add_u32_e32 v67, 39424, v66
	v_add_u32_e32 v68, 78848, v66
	v_add_u32_e32 v70, 39424, v69
	v_add_u32_e32 v71, 78848, v69
	v_add_u32_e32 v73, 39424, v72
	v_add_u32_e32 v74, 78848, v72
	v_add_u32_e32 v76, 39424, v75
	v_add_u32_e32 v77, 78848, v75
	s_waitcnt lgkmcnt(0)
	s_cmp_gt_u32 s9, 0xff
	s_cbranch_scc1 .Lsc5_done
.Lsc5_item:
	s_and_b32 s10, s9, 1
	s_lshr_b32 s3, s9, 1
	s_and_b32 s3, s3, 3
	s_lshr_b32 s4, s9, 5
	s_lshr_b32 s5, s9, 3
	s_and_b32 s5, s5, 3
	s_cmp_eq_u32 s10, 0
	s_cselect_b32 s15, 1, -1
	s_cselect_b32 s64, 0, 3
	s_cselect_b32 s65, -4, 0x43
	s_lshl_b32 s16, s4, 2
	s_add_u32 s16, s16, 0x200
	s_lshl_b32 s17, s4, 6
	s_add_u32 s16, s16, s64
	s_add_i32 s17, s17, s65
	s_lshl_b32 s3, s3, 8
	s_lshl_b32 s5, s5, 6
	s_cmp_eq_u32 s10, 0
	s_mov_b32 s65, 0x5100000
	s_cselect_b32 s64, s65, 0x7300000
	s_add_u32 s64, s64, s3
	s_add_u32 s18, s70, s64
	s_addc_u32 s19, s71, 0
	s_cmp_eq_u32 s10, 0
	s_mov_b32 s65, 0x9500000
	s_cselect_b32 s64, s65, 0xb700000
	s_add_u32 s64, s64, s3
	s_add_u32 s20, s70, s64
	s_addc_u32 s21, s71, 0
	s_add_u32 s64, s3, s5
	s_add_u32 s65, s64, 0xd900000
	s_add_u32 s22, s70, s65
	s_addc_u32 s23, s71, 0
	s_lshl_b32 s65, s10, 25
	s_add_u32 s64, s64, s65
	s_add_u32 s28, s68, s64
	s_addc_u32 s29, s69, 0
	s_mul_i32 s64, s10, 0x110000
	s_lshl_b32 s65, s3, 1
	s_add_u32 s64, s64, s65
	s_add_u32 s64, s64, 0x15b00000
	s_add_u32 s24, s70, s64
	s_addc_u32 s25, s71, 0
	s_add_u32 s26, s24, 0x220000
	s_addc_u32 s27, s25, 0
	s_lshl_b32 s64, s9, 16
	s_add_u32 s64, s64, 0xd00000
	s_add_u32 s30, s70, s64
	s_addc_u32 s31, s71, 0
	s_mul_i32 s5, s10, 63
	s_lshl_b32 s3, s7, 4
	v_add_u32_e32 v1, s3, v58
	v_xor_b32_e32 v1, s5, v1
	v_lshlrev_b32_e32 v1, 10, v1
	s_lshl_b32 s3, s8, 5
	v_lshl_add_u32 v57, v59, 3, v1
	v_add_u32_e32 v57, s3, v57
	v_lshrrev_b32_e32 v1, 4, v0
	v_xor_b32_e32 v93, s5, v1
	v_lshlrev_b32_e32 v93, 10, v93
	v_lshl_add_u32 v53, v58, 4, v93
	v_add_u32_e32 v1, 32, v1
	v_xor_b32_e32 v93, s5, v1
	v_lshlrev_b32_e32 v93, 10, v93
	v_lshl_add_u32 v54, v58, 4, v93
	v_lshrrev_b32_e32 v1, 3, v0
	v_xor_b32_e32 v1, s5, v1
	v_lshlrev_b32_e32 v1, 10, v1
	v_and_b32_e32 v93, 7, v0
	v_lshl_add_u32 v55, v93, 3, v1
	v_mov_b32_e32 v42, 0
	v_mov_b32_e32 v43, 0
	v_mov_b32_e32 v44, 0
	v_mov_b32_e32 v45, 0
	v_mov_b32_e32 v46, 0
	v_mov_b32_e32 v47, 0
	v_mov_b32_e32 v48, 0
	v_mov_b32_e32 v49, 0
	v_mov_b32_e32 v52, 0
	v_mov_b32_e32 v160, 0
	v_mov_b32_e32 v161, 0
	v_mov_b32_e32 v162, 0
	v_mov_b32_e32 v163, 0
	v_mov_b32_e32 v176, 0
	v_mov_b32_e32 v177, 0
	s_mov_b32 s3, 0
	s_cmp_lt_u32 s3, 4
	s_cselect_b32 s4, s16, s17
	s_mul_i32 s5, s3, s15
	s_add_i32 s4, s4, s5
	s_lshl_b32 s5, s4, 16
	s_lshl_b32 s4, s4, 11
	s_add_u32 s40, s18, s5
	s_addc_u32 s41, s19, 0
	s_add_u32 s42, s20, s5
	s_addc_u32 s43, s21, 0
	s_add_u32 s44, s22, s5
	s_addc_u32 s45, s23, 0
	s_add_u32 s46, s24, s4
	s_addc_u32 s47, s25, 0
	s_add_u32 s50, s26, s4
	s_addc_u32 s51, s27, 0
	global_load_dwordx4 v[2:5], v53, s[40:41]
	global_load_dwordx4 v[6:9], v54, s[40:41]
	global_load_dwordx4 v[10:13], v53, s[42:43]
	global_load_dwordx4 v[14:17], v54, s[42:43]
	global_load_dwordx2 v[18:19], v55, s[44:45]
	global_load_dword v20, v56, s[46:47]
	global_load_dword v21, v56, s[50:51]
	s_mov_b32 s3, 1
	s_cmp_lt_u32 s3, 4
	s_cselect_b32 s4, s16, s17
	s_mul_i32 s5, s3, s15
	s_add_i32 s4, s4, s5
	s_lshl_b32 s5, s4, 16
	s_lshl_b32 s4, s4, 11
	s_add_u32 s40, s18, s5
	s_addc_u32 s41, s19, 0
	s_add_u32 s42, s20, s5
	s_addc_u32 s43, s21, 0
	s_add_u32 s44, s22, s5
	s_addc_u32 s45, s23, 0
	s_add_u32 s46, s24, s4
	s_addc_u32 s47, s25, 0
	s_add_u32 s50, s26, s4
	s_addc_u32 s51, s27, 0
	global_load_dwordx4 v[22:25], v53, s[40:41]
	global_load_dwordx4 v[26:29], v54, s[40:41]
	global_load_dwordx4 v[30:33], v53, s[42:43]
	global_load_dwordx4 v[34:37], v54, s[42:43]
	global_load_dwordx2 v[38:39], v55, s[44:45]
	global_load_dword v40, v56, s[46:47]
	global_load_dword v41, v56, s[50:51]
	s_waitcnt vmcnt(0)
	ds_write_b128 v60, v[2:5] offset:0
	ds_write_b128 v60, v[6:9] offset:8704
	ds_write_b128 v60, v[10:13] offset:17408
	ds_write_b128 v60, v[14:17] offset:26112
	ds_write_b64 v63, v[18:19] offset:34816
	v_add_f32_e32 v92, v20, v52
	v_mul_f32_e32 v92, 0x3fb8aa3b, v92
	v_exp_f32_e32 v92, v92
	v_mov_b32_e32 v52, v21
	ds_write_b32 v78, v92 offset:0
	ds_write_b128 v61, v[22:25] offset:0
	ds_write_b128 v61, v[26:29] offset:8704
	ds_write_b128 v61, v[30:33] offset:17408
	ds_write_b128 v61, v[34:37] offset:26112
	ds_write_b64 v64, v[38:39] offset:34816
	v_add_f32_e32 v92, v40, v52
	v_mul_f32_e32 v92, 0x3fb8aa3b, v92
	v_exp_f32_e32 v92, v92
	v_mov_b32_e32 v52, v41
	ds_write_b32 v78, v92 offset:512
	s_mov_b32 s3, 2
	s_cmp_lt_u32 s3, 4
	s_cselect_b32 s4, s16, s17
	s_mul_i32 s5, s3, s15
	s_add_i32 s4, s4, s5
	s_lshl_b32 s5, s4, 16
	s_lshl_b32 s4, s4, 11
	s_add_u32 s40, s18, s5
	s_addc_u32 s41, s19, 0
	s_add_u32 s42, s20, s5
	s_addc_u32 s43, s21, 0
	s_add_u32 s44, s22, s5
	s_addc_u32 s45, s23, 0
	s_add_u32 s46, s24, s4
	s_addc_u32 s47, s25, 0
	s_add_u32 s50, s26, s4
	s_addc_u32 s51, s27, 0
	global_load_dwordx4 v[180:183], v53, s[40:41]
	global_load_dwordx4 v[184:187], v54, s[40:41]
	global_load_dwordx4 v[188:191], v53, s[42:43]
	global_load_dwordx4 v[192:195], v54, s[42:43]
	global_load_dwordx2 v[196:197], v55, s[44:45]
	global_load_dword v198, v56, s[46:47]
	global_load_dword v199, v56, s[50:51]
	global_store_dwordx2 v57, v[176:177], s[30:31]
	s_mov_b32 s3, 3
	s_cmp_lt_u32 s3, 4
	s_cselect_b32 s4, s16, s17
	s_mul_i32 s5, s3, s15
	s_add_i32 s4, s4, s5
	s_lshl_b32 s5, s4, 16
	s_lshl_b32 s4, s4, 11
	s_add_u32 s40, s18, s5
	s_addc_u32 s41, s19, 0
	s_add_u32 s42, s20, s5
	s_addc_u32 s43, s21, 0
	s_add_u32 s44, s22, s5
	s_addc_u32 s45, s23, 0
	s_add_u32 s46, s24, s4
	s_addc_u32 s47, s25, 0
	s_add_u32 s50, s26, s4
	s_addc_u32 s51, s27, 0
	global_load_dwordx4 v[2:5], v53, s[40:41]
	global_load_dwordx4 v[6:9], v54, s[40:41]
	global_load_dwordx4 v[10:13], v53, s[42:43]
	global_load_dwordx4 v[14:17], v54, s[42:43]
	global_load_dwordx2 v[18:19], v55, s[44:45]
	global_load_dword v20, v56, s[46:47]
	global_load_dword v21, v56, s[50:51]
	global_store_dwordx2 v57, v[176:177], s[30:31]
	s_waitcnt lgkmcnt(0)
	s_barrier
	ds_read_b32 v50, v79 offset:0
	ds_read_b32 v51, v79 offset:64
	ds_read_b128 v[96:99], v66 offset:0
	ds_read_b128 v[100:103], v66 offset:64
	ds_read_b128 v[104:107], v66 offset:128
	ds_read_b128 v[108:111], v66 offset:192
	ds_read_b128 v[216:219], v69 offset:17408
	ds_read_b128 v[220:223], v69 offset:17472
	ds_read_b128 v[224:227], v69 offset:17536
	ds_read_b128 v[228:231], v69 offset:17600
	s_cmp_eq_u32 s14, 0
	s_cbranch_scc1 .Lsc5_noy_p
	ds_read_b128 v[232:235], v69 offset:26112
	ds_read_b128 v[236:239], v69 offset:26176
	ds_read_b128 v[240:243], v69 offset:26240
	ds_read_b128 v[244:247], v69 offset:26304
.Lsc5_noy_p:
	s_waitcnt lgkmcnt(0)
	v_mfma_f32_16x16x32_bf16 v[152:155], v[216:219], v[96:99], 0
	v_mfma_f32_16x16x32_bf16 v[152:155], v[220:223], v[100:103], v[152:155]
	v_mfma_f32_16x16x32_bf16 v[152:155], v[224:227], v[104:107], v[152:155]
	v_mfma_f32_16x16x32_bf16 v[152:155], v[228:231], v[108:111], v[152:155]
	s_cmp_eq_u32 s14, 0
	s_cbranch_scc1 .Lsc5_noy2_p
	v_mfma_f32_16x16x32_bf16 v[156:159], v[232:235], v[96:99], 0
	v_mfma_f32_16x16x32_bf16 v[156:159], v[236:239], v[100:103], v[156:159]
	v_mfma_f32_16x16x32_bf16 v[156:159], v[240:243], v[104:107], v[156:159]
	v_mfma_f32_16x16x32_bf16 v[156:159], v[244:247], v[108:111], v[156:159]
.Lsc5_noy2_p:
	v_mul_f32_e32 v42, v42, v50
	v_mul_f32_e32 v43, v43, v50
	v_mul_f32_e32 v44, v44, v50
	v_mul_f32_e32 v45, v45, v50
	v_mul_f32_e32 v46, v46, v51
	v_mul_f32_e32 v47, v47, v51
	v_mul_f32_e32 v48, v48, v51
	v_mul_f32_e32 v49, v49, v51
	v_cvt_pk_bf16_f32 v88, v42, v43
	v_cvt_pk_bf16_f32 v89, v44, v45
	v_cvt_pk_bf16_f32 v90, v46, v47
	v_cvt_pk_bf16_f32 v91, v48, v49
	ds_write_b64 v80, v[88:89]
	ds_write_b64 v80, v[90:91] offset:1152
	v_cndmask_b32_e64 v152, 0, v152, s[76:77]
	v_cndmask_b32_e64 v153, 0, v153, s[78:79]
	v_cndmask_b32_e64 v154, 0, v154, s[80:81]
	v_cndmask_b32_e64 v155, 0, v155, s[82:83]
	v_cvt_pk_bf16_f32 v160, v152, v153
	v_cvt_pk_bf16_f32 v161, v154, v155
	s_cmp_eq_u32 s14, 0
	s_cbranch_scc1 .Lsc5_noy3_p
	v_cndmask_b32_e64 v156, 0, v156, s[84:85]
	v_cndmask_b32_e64 v157, 0, v157, s[88:89]
	v_cndmask_b32_e64 v158, 0, v158, s[90:91]
	v_cndmask_b32_e64 v159, 0, v159, s[92:93]
	v_cvt_pk_bf16_f32 v162, v156, v157
	v_cvt_pk_bf16_f32 v163, v158, v159

.Lsc5_loop:
	ds_read_b32 v50, v79 offset:512
	ds_read_b32 v51, v79 offset:576
	ds_read_b64_tr_b16 v[128:129], v72 offset:34816
	ds_read_b64_tr_b16 v[130:131], v72 offset:35968
	ds_read_b64_tr_b16 v[132:133], v72 offset:37120
	ds_read_b64_tr_b16 v[134:135], v72 offset:38272
	ds_read_b64_tr_b16 v[136:137], v75 offset:17408
	ds_read_b64_tr_b16 v[138:139], v75 offset:21760
	ds_read_b64_tr_b16 v[140:141], v75 offset:17440
	ds_read_b64_tr_b16 v[142:143], v75 offset:21792
	ds_read_b64_tr_b16 v[144:145], v75 offset:26112
	ds_read_b64_tr_b16 v[146:147], v75 offset:30464
	ds_read_b64_tr_b16 v[148:149], v75 offset:26144
	ds_read_b64_tr_b16 v[150:151], v75 offset:30496
	s_add_u32 s3, s34, 4
	s_min_u32 s3, s3, 67
	s_cmp_lt_u32 s3, 4
	s_cselect_b32 s4, s16, s17
	s_mul_i32 s5, s3, s15
	s_add_i32 s4, s4, s5
	s_lshl_b32 s5, s4, 16
	s_lshl_b32 s4, s4, 11
	s_add_u32 s40, s18, s5
	s_addc_u32 s41, s19, 0
	s_add_u32 s42, s20, s5
	s_addc_u32 s43, s21, 0
	s_add_u32 s44, s22, s5
	s_addc_u32 s45, s23, 0
	s_add_u32 s46, s24, s4
	s_addc_u32 s47, s25, 0
	s_add_u32 s50, s26, s4
	s_addc_u32 s51, s27, 0
	global_load_dwordx4 v[22:25], v53, s[40:41]
	global_load_dwordx4 v[26:29], v54, s[40:41]
	global_load_dwordx4 v[30:33], v53, s[42:43]
	global_load_dwordx4 v[34:37], v54, s[42:43]
	global_load_dwordx2 v[38:39], v55, s[44:45]
	global_load_dword v40, v56, s[46:47]
	global_load_dword v41, v56, s[50:51]
	s_waitcnt lgkmcnt(6)
	v_mfma_f32_16x16x32_bf16 v[42:45], v[128:131], v[136:139], v[42:45]
	ds_read_b64_tr_b16 v[112:113], v82 offset:0
	ds_read_b64_tr_b16 v[114:115], v82 offset:288
	ds_read_b64_tr_b16 v[116:117], v82 offset:2304
	ds_read_b64_tr_b16 v[118:119], v82 offset:2592
	s_waitcnt lgkmcnt(8)
	v_mfma_f32_16x16x32_bf16 v[46:49], v[128:131], v[140:143], v[46:49]
	ds_read_b64_tr_b16 v[120:121], v82 offset:4608
	ds_read_b64_tr_b16 v[122:123], v82 offset:4896
	ds_read_b64_tr_b16 v[124:125], v82 offset:6912
	ds_read_b64_tr_b16 v[126:127], v82 offset:7200
	s_waitcnt lgkmcnt(10)
	v_mfma_f32_16x16x32_bf16 v[42:45], v[132:135], v[144:147], v[42:45]
	ds_read_b128 v[164:167], v86
	ds_read_b128 v[168:171], v86 offset:1024
	s_waitcnt lgkmcnt(10)
	v_mfma_f32_16x16x32_bf16 v[46:49], v[132:135], v[148:151], v[46:49]
	s_waitcnt vmcnt(16)
	ds_write_b128 v62, v[180:183] offset:0
	ds_write_b128 v62, v[184:187] offset:8704
	s_waitcnt lgkmcnt(10)
	v_mfma_f32_16x16x32_bf16 v[172:175], v[112:115], v[96:99], 0
	ds_write_b128 v62, v[188:191] offset:17408
	ds_write_b128 v62, v[192:195] offset:26112
	s_waitcnt lgkmcnt(10)
	v_mfma_f32_16x16x32_bf16 v[172:175], v[116:119], v[100:103], v[172:175]
	ds_write_b64 v65, v[196:197] offset:34816
	v_add_f32_e32 v92, v198, v52
	v_mul_f32_e32 v92, 0x3fb8aa3b, v92
	v_exp_f32_e32 v92, v92
	v_mov_b32_e32 v52, v199
	ds_write_b32 v78, v92 offset:1024
	s_waitcnt lgkmcnt(10)
	v_mfma_f32_16x16x32_bf16 v[172:175], v[120:123], v[104:107], v[172:175]
	ds_read_b128 v[200:203], v67 offset:0
	ds_read_b128 v[204:207], v67 offset:64
	s_waitcnt lgkmcnt(10)
	v_mfma_f32_16x16x32_bf16 v[172:175], v[124:127], v[108:111], v[172:175]
	ds_read_b128 v[208:211], v67 offset:128
	ds_read_b128 v[212:215], v67 offset:192
	s_waitcnt lgkmcnt(11)
	v_mfma_f32_16x16x32_bf16 v[172:175], v[128:131], v[164:167], v[172:175]
	ds_read_b128 v[216:219], v70 offset:17408
	ds_read_b128 v[220:223], v70 offset:17472
	ds_read_b128 v[224:227], v70 offset:17536
	ds_read_b128 v[228:231], v70 offset:17600
	s_waitcnt lgkmcnt(14)
	s_cmp_eq_u32 s11, 0
	s_cbranch_scc1 .Lsc5_nopv1_0
	v_mfma_f32_16x16x32_bf16 v[172:175], v[132:135], v[168:171], v[172:175]
.Lsc5_nopv1_0:
	s_waitcnt lgkmcnt(8)
	s_cmp_eq_u32 s14, 0
	s_cbranch_scc1 .Lsc5_noy_0
	ds_read_b128 v[232:235], v70 offset:26112
	ds_read_b128 v[236:239], v70 offset:26176
	ds_read_b128 v[240:243], v70 offset:26240
	ds_read_b128 v[244:247], v70 offset:26304
.Lsc5_noy_0:
	v_mul_f32_e32 v42, v42, v50
	v_mul_f32_e32 v43, v43, v50
	v_mul_f32_e32 v44, v44, v50
	v_mul_f32_e32 v45, v45, v50
	v_mul_f32_e32 v46, v46, v51
	v_mul_f32_e32 v47, v47, v51
	v_mul_f32_e32 v48, v48, v51
	v_mul_f32_e32 v49, v49, v51
	v_cvt_pk_bf16_f32 v88, v42, v43
	v_cvt_pk_bf16_f32 v89, v44, v45
	v_cvt_pk_bf16_f32 v90, v46, v47
	v_cvt_pk_bf16_f32 v91, v48, v49
	ds_write_b64 v81, v[88:89]
	ds_write_b64 v81, v[90:91] offset:1152
	s_add_u32 s3, s34, 0
	s_cmp_lt_u32 s3, 4
	s_cselect_b32 s4, s16, s17
	s_mul_i32 s5, s3, s15
	s_add_i32 s4, s4, s5
	s_lshl_b32 s4, s4, 16
	s_add_u32 s64, s28, s4
	s_addc_u32 s65, s29, 0
	s_cmp_eq_u32 s34, 0
	s_cselect_b32 s64, s30, s64
	s_cselect_b32 s65, s31, s65
	v_cvt_pk_bf16_f32 v176, v172, v173
	v_cvt_pk_bf16_f32 v177, v174, v175
	s_waitcnt lgkmcnt(2)
	v_mfma_f32_16x16x32_bf16 v[152:155], v[216:219], v[200:203], 0
	v_mfma_f32_16x16x32_bf16 v[152:155], v[220:223], v[204:207], v[152:155]
	v_mfma_f32_16x16x32_bf16 v[152:155], v[224:227], v[208:211], v[152:155]
	v_mfma_f32_16x16x32_bf16 v[152:155], v[228:231], v[212:215], v[152:155]
	s_waitcnt lgkmcnt(0)
	s_cmp_eq_u32 s14, 0
	s_cbranch_scc1 .Lsc5_noy2_0
	v_mfma_f32_16x16x32_bf16 v[156:159], v[232:235], v[200:203], 0
	v_mfma_f32_16x16x32_bf16 v[156:159], v[236:239], v[204:207], v[156:159]
	v_mfma_f32_16x16x32_bf16 v[156:159], v[240:243], v[208:211], v[156:159]
	v_mfma_f32_16x16x32_bf16 v[156:159], v[244:247], v[212:215], v[156:159]
.Lsc5_noy2_0:
	global_store_dwordx2 v57, v[176:177], s[64:65]
	v_cndmask_b32_e64 v152, 0, v152, s[76:77]
	v_cndmask_b32_e64 v153, 0, v153, s[78:79]
	v_cndmask_b32_e64 v154, 0, v154, s[80:81]
	v_cndmask_b32_e64 v155, 0, v155, s[82:83]
	v_cvt_pk_bf16_f32 v160, v152, v153
	v_cvt_pk_bf16_f32 v161, v154, v155
	s_cmp_eq_u32 s14, 0
	s_cbranch_scc1 .Lsc5_noy3_0
	v_cndmask_b32_e64 v156, 0, v156, s[84:85]
	v_cndmask_b32_e64 v157, 0, v157, s[88:89]
	v_cndmask_b32_e64 v158, 0, v158, s[90:91]
	v_cndmask_b32_e64 v159, 0, v159, s[92:93]
	v_cvt_pk_bf16_f32 v162, v156, v157
	v_cvt_pk_bf16_f32 v163, v158, v159
.Lsc5_noy3_0:
	ds_write_b64 v85, v[160:161]
	ds_write_b64 v85, v[162:163] offset:1024
	s_waitcnt lgkmcnt(0)
	s_barrier
	ds_read_b32 v50, v79 offset:1024
	ds_read_b32 v51, v79 offset:1088
	ds_read_b64_tr_b16 v[128:129], v73 offset:34816
	ds_read_b64_tr_b16 v[130:131], v73 offset:35968
	ds_read_b64_tr_b16 v[132:133], v73 offset:37120
	ds_read_b64_tr_b16 v[134:135], v73 offset:38272
	ds_read_b64_tr_b16 v[136:137], v76 offset:17408
	ds_read_b64_tr_b16 v[138:139], v76 offset:21760
	ds_read_b64_tr_b16 v[140:141], v76 offset:17440
	ds_read_b64_tr_b16 v[142:143], v76 offset:21792
	ds_read_b64_tr_b16 v[144:145], v76 offset:26112
	ds_read_b64_tr_b16 v[146:147], v76 offset:30464
	ds_read_b64_tr_b16 v[148:149], v76 offset:26144
	ds_read_b64_tr_b16 v[150:151], v76 offset:30496
	s_add_u32 s3, s34, 5
	s_min_u32 s3, s3, 67
	s_cmp_lt_u32 s3, 4
	s_cselect_b32 s4, s16, s17
	s_mul_i32 s5, s3, s15
	s_add_i32 s4, s4, s5
	s_lshl_b32 s5, s4, 16
	s_lshl_b32 s4, s4, 11
	s_add_u32 s40, s18, s5
	s_addc_u32 s41, s19, 0
	s_add_u32 s42, s20, s5
	s_addc_u32 s43, s21, 0
	s_add_u32 s44, s22, s5
	s_addc_u32 s45, s23, 0
	s_add_u32 s46, s24, s4
	s_addc_u32 s47, s25, 0
	s_add_u32 s50, s26, s4
	s_addc_u32 s51, s27, 0
	global_load_dwordx4 v[180:183], v53, s[40:41]
	global_load_dwordx4 v[184:187], v54, s[40:41]
	global_load_dwordx4 v[188:191], v53, s[42:43]
	global_load_dwordx4 v[192:195], v54, s[42:43]
	global_load_dwordx2 v[196:197], v55, s[44:45]
	global_load_dword v198, v56, s[46:47]
	global_load_dword v199, v56, s[50:51]
	s_waitcnt lgkmcnt(6)
	v_mfma_f32_16x16x32_bf16 v[42:45], v[128:131], v[136:139], v[42:45]
	ds_read_b64_tr_b16 v[112:113], v83 offset:0
	ds_read_b64_tr_b16 v[114:115], v83 offset:288
	ds_read_b64_tr_b16 v[116:117], v83 offset:2304
	ds_read_b64_tr_b16 v[118:119], v83 offset:2592
	s_waitcnt lgkmcnt(8)
	v_mfma_f32_16x16x32_bf16 v[46:49], v[128:131], v[140:143], v[46:49]
	ds_read_b64_tr_b16 v[120:121], v83 offset:4608
	ds_read_b64_tr_b16 v[122:123], v83 offset:4896
	ds_read_b64_tr_b16 v[124:125], v83 offset:6912
	ds_read_b64_tr_b16 v[126:127], v83 offset:7200
	s_waitcnt lgkmcnt(10)
	v_mfma_f32_16x16x32_bf16 v[42:45], v[132:135], v[144:147], v[42:45]
	ds_read_b128 v[164:167], v87
	ds_read_b128 v[168:171], v87 offset:1024
	s_waitcnt lgkmcnt(10)
	v_mfma_f32_16x16x32_bf16 v[46:49], v[132:135], v[148:151], v[46:49]
	s_waitcnt vmcnt(16)
	ds_write_b128 v60, v[2:5] offset:0
	ds_write_b128 v60, v[6:9] offset:8704
	s_waitcnt lgkmcnt(10)
	v_mfma_f32_16x16x32_bf16 v[172:175], v[112:115], v[200:203], 0
	ds_write_b128 v60, v[10:13] offset:17408
	ds_write_b128 v60, v[14:17] offset:26112
	s_waitcnt lgkmcnt(10)
	v_mfma_f32_16x16x32_bf16 v[172:175], v[116:119], v[204:207], v[172:175]
	ds_write_b64 v63, v[18:19] offset:34816
	v_add_f32_e32 v92, v20, v52
	v_mul_f32_e32 v92, 0x3fb8aa3b, v92
	v_exp_f32_e32 v92, v92
	v_mov_b32_e32 v52, v21
	ds_write_b32 v78, v92 offset:0
	s_waitcnt lgkmcnt(10)
	v_mfma_f32_16x16x32_bf16 v[172:175], v[120:123], v[208:211], v[172:175]
	ds_read_b128 v[96:99], v68 offset:0
	ds_read_b128 v[100:103], v68 offset:64
	s_waitcnt lgkmcnt(10)
	v_mfma_f32_16x16x32_bf16 v[172:175], v[124:127], v[212:215], v[172:175]
	ds_read_b128 v[104:107], v68 offset:128
	ds_read_b128 v[108:111], v68 offset:192
	s_waitcnt lgkmcnt(11)
	v_mfma_f32_16x16x32_bf16 v[172:175], v[128:131], v[164:167], v[172:175]
	ds_read_b128 v[216:219], v71 offset:17408
	ds_read_b128 v[220:223], v71 offset:17472
	ds_read_b128 v[224:227], v71 offset:17536
	ds_read_b128 v[228:231], v71 offset:17600
	s_waitcnt lgkmcnt(14)
	s_cmp_eq_u32 s11, 0
	s_cbranch_scc1 .Lsc5_nopv1_1
	v_mfma_f32_16x16x32_bf16 v[172:175], v[132:135], v[168:171], v[172:175]
.Lsc5_nopv1_1:
	s_waitcnt lgkmcnt(8)
	s_cmp_eq_u32 s14, 0
	s_cbranch_scc1 .Lsc5_noy_1
	ds_read_b128 v[232:235], v71 offset:26112
	ds_read_b128 v[236:239], v71 offset:26176
	ds_read_b128 v[240:243], v71 offset:26240
	ds_read_b128 v[244:247], v71 offset:26304
.Lsc5_noy_1:
	v_mul_f32_e32 v42, v42, v50
	v_mul_f32_e32 v43, v43, v50
	v_mul_f32_e32 v44, v44, v50
	v_mul_f32_e32 v45, v45, v50
	v_mul_f32_e32 v46, v46, v51
	v_mul_f32_e32 v47, v47, v51
	v_mul_f32_e32 v48, v48, v51
	v_mul_f32_e32 v49, v49, v51
	v_cvt_pk_bf16_f32 v88, v42, v43
	v_cvt_pk_bf16_f32 v89, v44, v45
	v_cvt_pk_bf16_f32 v90, v46, v47
	v_cvt_pk_bf16_f32 v91, v48, v49
	ds_write_b64 v80, v[88:89]
	ds_write_b64 v80, v[90:91] offset:1152
	s_add_u32 s3, s34, 1
	s_cmp_lt_u32 s3, 4
	s_cselect_b32 s4, s16, s17
	s_mul_i32 s5, s3, s15
	s_add_i32 s4, s4, s5
	s_lshl_b32 s4, s4, 16
	s_add_u32 s64, s28, s4
	s_addc_u32 s65, s29, 0
	s_cmp_eq_u32 s34, 0
	s_cselect_b32 s64, s30, s64
	s_cselect_b32 s65, s31, s65
	v_cvt_pk_bf16_f32 v176, v172, v173
	v_cvt_pk_bf16_f32 v177, v174, v175
	s_waitcnt lgkmcnt(2)
	v_mfma_f32_16x16x32_bf16 v[152:155], v[216:219], v[96:99], 0
	v_mfma_f32_16x16x32_bf16 v[152:155], v[220:223], v[100:103], v[152:155]
	v_mfma_f32_16x16x32_bf16 v[152:155], v[224:227], v[104:107], v[152:155]
	v_mfma_f32_16x16x32_bf16 v[152:155], v[228:231], v[108:111], v[152:155]
	s_waitcnt lgkmcnt(0)
	s_cmp_eq_u32 s14, 0
	s_cbranch_scc1 .Lsc5_noy2_1
	v_mfma_f32_16x16x32_bf16 v[156:159], v[232:235], v[96:99], 0
	v_mfma_f32_16x16x32_bf16 v[156:159], v[236:239], v[100:103], v[156:159]
	v_mfma_f32_16x16x32_bf16 v[156:159], v[240:243], v[104:107], v[156:159]
	v_mfma_f32_16x16x32_bf16 v[156:159], v[244:247], v[108:111], v[156:159]

.Lsc5_noy3_1:
	ds_write_b64 v84, v[160:161]
	ds_write_b64 v84, v[162:163] offset:1024
	s_waitcnt lgkmcnt(0)
	s_barrier
	ds_read_b32 v50, v79 offset:0
	ds_read_b32 v51, v79 offset:64
	ds_read_b64_tr_b16 v[128:129], v74 offset:34816
	ds_read_b64_tr_b16 v[130:131], v74 offset:35968
	ds_read_b64_tr_b16 v[132:133], v74 offset:37120
	ds_read_b64_tr_b16 v[134:135], v74 offset:38272
	ds_read_b64_tr_b16 v[136:137], v77 offset:17408
	ds_read_b64_tr_b16 v[138:139], v77 offset:21760
	ds_read_b64_tr_b16 v[140:141], v77 offset:17440
	ds_read_b64_tr_b16 v[142:143], v77 offset:21792
	ds_read_b64_tr_b16 v[144:145], v77 offset:26112
	ds_read_b64_tr_b16 v[146:147], v77 offset:30464
	ds_read_b64_tr_b16 v[148:149], v77 offset:26144
	ds_read_b64_tr_b16 v[150:151], v77 offset:30496
	s_add_u32 s3, s34, 6
	s_min_u32 s3, s3, 67
	s_cmp_lt_u32 s3, 4
	s_cselect_b32 s4, s16, s17
	s_mul_i32 s5, s3, s15
	s_add_i32 s4, s4, s5
	s_lshl_b32 s5, s4, 16
	s_lshl_b32 s4, s4, 11
	s_add_u32 s40, s18, s5
	s_addc_u32 s41, s19, 0
	s_add_u32 s42, s20, s5
	s_addc_u32 s43, s21, 0
	s_add_u32 s44, s22, s5
	s_addc_u32 s45, s23, 0
	s_add_u32 s46, s24, s4
	s_addc_u32 s47, s25, 0
	s_add_u32 s50, s26, s4
	s_addc_u32 s51, s27, 0
	global_load_dwordx4 v[2:5], v53, s[40:41]
	global_load_dwordx4 v[6:9], v54, s[40:41]
	global_load_dwordx4 v[10:13], v53, s[42:43]
	global_load_dwordx4 v[14:17], v54, s[42:43]
	global_load_dwordx2 v[18:19], v55, s[44:45]
	global_load_dword v20, v56, s[46:47]
	global_load_dword v21, v56, s[50:51]
	s_waitcnt lgkmcnt(6)
	v_mfma_f32_16x16x32_bf16 v[42:45], v[128:131], v[136:139], v[42:45]
	ds_read_b64_tr_b16 v[112:113], v82 offset:0
	ds_read_b64_tr_b16 v[114:115], v82 offset:288
	ds_read_b64_tr_b16 v[116:117], v82 offset:2304
	ds_read_b64_tr_b16 v[118:119], v82 offset:2592
	s_waitcnt lgkmcnt(8)
	v_mfma_f32_16x16x32_bf16 v[46:49], v[128:131], v[140:143], v[46:49]
	ds_read_b64_tr_b16 v[120:121], v82 offset:4608
	ds_read_b64_tr_b16 v[122:123], v82 offset:4896
	ds_read_b64_tr_b16 v[124:125], v82 offset:6912
	ds_read_b64_tr_b16 v[126:127], v82 offset:7200
	s_waitcnt lgkmcnt(10)
	v_mfma_f32_16x16x32_bf16 v[42:45], v[132:135], v[144:147], v[42:45]
	ds_read_b128 v[164:167], v86
	ds_read_b128 v[168:171], v86 offset:1024
	s_waitcnt lgkmcnt(10)
	v_mfma_f32_16x16x32_bf16 v[46:49], v[132:135], v[148:151], v[46:49]
	s_waitcnt vmcnt(16)
	ds_write_b128 v61, v[22:25] offset:0
	ds_write_b128 v61, v[26:29] offset:8704
	s_waitcnt lgkmcnt(10)
	v_mfma_f32_16x16x32_bf16 v[172:175], v[112:115], v[96:99], 0
	ds_write_b128 v61, v[30:33] offset:17408
	ds_write_b128 v61, v[34:37] offset:26112
	s_waitcnt lgkmcnt(10)
	v_mfma_f32_16x16x32_bf16 v[172:175], v[116:119], v[100:103], v[172:175]
	ds_write_b64 v64, v[38:39] offset:34816
	v_add_f32_e32 v92, v40, v52
	v_mul_f32_e32 v92, 0x3fb8aa3b, v92
	v_exp_f32_e32 v92, v92
	v_mov_b32_e32 v52, v41
	ds_write_b32 v78, v92 offset:512
	s_waitcnt lgkmcnt(10)
	v_mfma_f32_16x16x32_bf16 v[172:175], v[120:123], v[104:107], v[172:175]
	ds_read_b128 v[200:203], v66 offset:0
	ds_read_b128 v[204:207], v66 offset:64
	s_waitcnt lgkmcnt(10)
	v_mfma_f32_16x16x32_bf16 v[172:175], v[124:127], v[108:111], v[172:175]
	ds_read_b128 v[208:211], v66 offset:128
	ds_read_b128 v[212:215], v66 offset:192
	s_waitcnt lgkmcnt(11)
	v_mfma_f32_16x16x32_bf16 v[172:175], v[128:131], v[164:167], v[172:175]
	ds_read_b128 v[216:219], v69 offset:17408
	ds_read_b128 v[220:223], v69 offset:17472
	ds_read_b128 v[224:227], v69 offset:17536
	ds_read_b128 v[228:231], v69 offset:17600
	s_waitcnt lgkmcnt(14)
	s_cmp_eq_u32 s11, 0
	s_cbranch_scc1 .Lsc5_nopv1_2
	v_mfma_f32_16x16x32_bf16 v[172:175], v[132:135], v[168:171], v[172:175]
.Lsc5_nopv1_2:
	s_waitcnt lgkmcnt(8)
	s_cmp_eq_u32 s14, 0
	s_cbranch_scc1 .Lsc5_noy_2
	ds_read_b128 v[232:235], v69 offset:26112
	ds_read_b128 v[236:239], v69 offset:26176
	ds_read_b128 v[240:243], v69 offset:26240
	ds_read_b128 v[244:247], v69 offset:26304
.Lsc5_noy_2:
	v_mul_f32_e32 v42, v42, v50
	v_mul_f32_e32 v43, v43, v50
	v_mul_f32_e32 v44, v44, v50
	v_mul_f32_e32 v45, v45, v50
	v_mul_f32_e32 v46, v46, v51
	v_mul_f32_e32 v47, v47, v51
	v_mul_f32_e32 v48, v48, v51
	v_mul_f32_e32 v49, v49, v51
	v_cvt_pk_bf16_f32 v88, v42, v43
	v_cvt_pk_bf16_f32 v89, v44, v45
	v_cvt_pk_bf16_f32 v90, v46, v47
	v_cvt_pk_bf16_f32 v91, v48, v49
	ds_write_b64 v81, v[88:89]
	ds_write_b64 v81, v[90:91] offset:1152
	s_add_u32 s3, s34, 2
	s_cmp_lt_u32 s3, 4
	s_cselect_b32 s4, s16, s17
	s_mul_i32 s5, s3, s15
	s_add_i32 s4, s4, s5
	s_lshl_b32 s4, s4, 16
	s_add_u32 s64, s28, s4
	s_addc_u32 s65, s29, 0
	s_cmp_eq_u32 s34, 0
	s_cselect_b32 s64, s30, s64
	s_cselect_b32 s65, s31, s65
	v_cvt_pk_bf16_f32 v176, v172, v173
	v_cvt_pk_bf16_f32 v177, v174, v175
	s_waitcnt lgkmcnt(2)
	v_mfma_f32_16x16x32_bf16 v[152:155], v[216:219], v[200:203], 0
	v_mfma_f32_16x16x32_bf16 v[152:155], v[220:223], v[204:207], v[152:155]
	v_mfma_f32_16x16x32_bf16 v[152:155], v[224:227], v[208:211], v[152:155]
	v_mfma_f32_16x16x32_bf16 v[152:155], v[228:231], v[212:215], v[152:155]
	s_waitcnt lgkmcnt(0)
	s_cmp_eq_u32 s14, 0
	s_cbranch_scc1 .Lsc5_noy2_2
	v_mfma_f32_16x16x32_bf16 v[156:159], v[232:235], v[200:203], 0
	v_mfma_f32_16x16x32_bf16 v[156:159], v[236:239], v[204:207], v[156:159]
	v_mfma_f32_16x16x32_bf16 v[156:159], v[240:243], v[208:211], v[156:159]
	v_mfma_f32_16x16x32_bf16 v[156:159], v[244:247], v[212:215], v[156:159]

.Lsc5_noy3_2:
	ds_write_b64 v85, v[160:161]
	ds_write_b64 v85, v[162:163] offset:1024
	s_waitcnt lgkmcnt(0)
	s_barrier
	ds_read_b32 v50, v79 offset:512
	ds_read_b32 v51, v79 offset:576
	ds_read_b64_tr_b16 v[128:129], v72 offset:34816
	ds_read_b64_tr_b16 v[130:131], v72 offset:35968
	ds_read_b64_tr_b16 v[132:133], v72 offset:37120
	ds_read_b64_tr_b16 v[134:135], v72 offset:38272
	ds_read_b64_tr_b16 v[136:137], v75 offset:17408
	ds_read_b64_tr_b16 v[138:139], v75 offset:21760
	ds_read_b64_tr_b16 v[140:141], v75 offset:17440
	ds_read_b64_tr_b16 v[142:143], v75 offset:21792
	ds_read_b64_tr_b16 v[144:145], v75 offset:26112
	ds_read_b64_tr_b16 v[146:147], v75 offset:30464
	ds_read_b64_tr_b16 v[148:149], v75 offset:26144
	ds_read_b64_tr_b16 v[150:151], v75 offset:30496
	s_add_u32 s3, s34, 7
	s_min_u32 s3, s3, 67
	s_cmp_lt_u32 s3, 4
	s_cselect_b32 s4, s16, s17
	s_mul_i32 s5, s3, s15
	s_add_i32 s4, s4, s5
	s_lshl_b32 s5, s4, 16
	s_lshl_b32 s4, s4, 11
	s_add_u32 s40, s18, s5
	s_addc_u32 s41, s19, 0
	s_add_u32 s42, s20, s5
	s_addc_u32 s43, s21, 0
	s_add_u32 s44, s22, s5
	s_addc_u32 s45, s23, 0
	s_add_u32 s46, s24, s4
	s_addc_u32 s47, s25, 0
	s_add_u32 s50, s26, s4
	s_addc_u32 s51, s27, 0
	global_load_dwordx4 v[22:25], v53, s[40:41]
	global_load_dwordx4 v[26:29], v54, s[40:41]
	global_load_dwordx4 v[30:33], v53, s[42:43]
	global_load_dwordx4 v[34:37], v54, s[42:43]
	global_load_dwordx2 v[38:39], v55, s[44:45]
	global_load_dword v40, v56, s[46:47]
	global_load_dword v41, v56, s[50:51]
	s_waitcnt lgkmcnt(6)
	v_mfma_f32_16x16x32_bf16 v[42:45], v[128:131], v[136:139], v[42:45]
	ds_read_b64_tr_b16 v[112:113], v83 offset:0
	ds_read_b64_tr_b16 v[114:115], v83 offset:288
	ds_read_b64_tr_b16 v[116:117], v83 offset:2304
	ds_read_b64_tr_b16 v[118:119], v83 offset:2592
	s_waitcnt lgkmcnt(8)
	v_mfma_f32_16x16x32_bf16 v[46:49], v[128:131], v[140:143], v[46:49]
	ds_read_b64_tr_b16 v[120:121], v83 offset:4608
	ds_read_b64_tr_b16 v[122:123], v83 offset:4896
	ds_read_b64_tr_b16 v[124:125], v83 offset:6912
	ds_read_b64_tr_b16 v[126:127], v83 offset:7200
	s_waitcnt lgkmcnt(10)
	v_mfma_f32_16x16x32_bf16 v[42:45], v[132:135], v[144:147], v[42:45]
	ds_read_b128 v[164:167], v87
	ds_read_b128 v[168:171], v87 offset:1024
	s_waitcnt lgkmcnt(10)
	v_mfma_f32_16x16x32_bf16 v[46:49], v[132:135], v[148:151], v[46:49]
	s_waitcnt vmcnt(16)
	ds_write_b128 v62, v[180:183] offset:0
	ds_write_b128 v62, v[184:187] offset:8704
	s_waitcnt lgkmcnt(10)
	v_mfma_f32_16x16x32_bf16 v[172:175], v[112:115], v[200:203], 0
	ds_write_b128 v62, v[188:191] offset:17408
	ds_write_b128 v62, v[192:195] offset:26112
	s_waitcnt lgkmcnt(10)
	v_mfma_f32_16x16x32_bf16 v[172:175], v[116:119], v[204:207], v[172:175]
	ds_write_b64 v65, v[196:197] offset:34816
	v_add_f32_e32 v92, v198, v52
	v_mul_f32_e32 v92, 0x3fb8aa3b, v92
	v_exp_f32_e32 v92, v92
	v_mov_b32_e32 v52, v199
	ds_write_b32 v78, v92 offset:1024
	s_waitcnt lgkmcnt(10)
	v_mfma_f32_16x16x32_bf16 v[172:175], v[120:123], v[208:211], v[172:175]
	ds_read_b128 v[96:99], v67 offset:0
	ds_read_b128 v[100:103], v67 offset:64
	s_waitcnt lgkmcnt(10)
	v_mfma_f32_16x16x32_bf16 v[172:175], v[124:127], v[212:215], v[172:175]
	ds_read_b128 v[104:107], v67 offset:128
	ds_read_b128 v[108:111], v67 offset:192
	s_waitcnt lgkmcnt(11)
	v_mfma_f32_16x16x32_bf16 v[172:175], v[128:131], v[164:167], v[172:175]
	ds_read_b128 v[216:219], v70 offset:17408
	ds_read_b128 v[220:223], v70 offset:17472
	ds_read_b128 v[224:227], v70 offset:17536
	ds_read_b128 v[228:231], v70 offset:17600
	s_waitcnt lgkmcnt(14)
	s_cmp_eq_u32 s11, 0
	s_cbranch_scc1 .Lsc5_nopv1_3
	v_mfma_f32_16x16x32_bf16 v[172:175], v[132:135], v[168:171], v[172:175]

.Lsc5_noy_3:
	v_mul_f32_e32 v42, v42, v50
	v_mul_f32_e32 v43, v43, v50
	v_mul_f32_e32 v44, v44, v50
	v_mul_f32_e32 v45, v45, v50
	v_mul_f32_e32 v46, v46, v51
	v_mul_f32_e32 v47, v47, v51
	v_mul_f32_e32 v48, v48, v51
	v_mul_f32_e32 v49, v49, v51
	v_cvt_pk_bf16_f32 v88, v42, v43
	v_cvt_pk_bf16_f32 v89, v44, v45
	v_cvt_pk_bf16_f32 v90, v46, v47
	v_cvt_pk_bf16_f32 v91, v48, v49
	ds_write_b64 v80, v[88:89]
	ds_write_b64 v80, v[90:91] offset:1152
	s_add_u32 s3, s34, 3
	s_cmp_lt_u32 s3, 4
	s_cselect_b32 s4, s16, s17
	s_mul_i32 s5, s3, s15
	s_add_i32 s4, s4, s5
	s_lshl_b32 s4, s4, 16
	s_add_u32 s64, s28, s4
	s_addc_u32 s65, s29, 0
	s_cmp_eq_u32 s34, 0
	s_cselect_b32 s64, s30, s64
	s_cselect_b32 s65, s31, s65
	v_cvt_pk_bf16_f32 v176, v172, v173
	v_cvt_pk_bf16_f32 v177, v174, v175
	s_waitcnt lgkmcnt(2)
	v_mfma_f32_16x16x32_bf16 v[152:155], v[216:219], v[96:99], 0
	v_mfma_f32_16x16x32_bf16 v[152:155], v[220:223], v[100:103], v[152:155]
	v_mfma_f32_16x16x32_bf16 v[152:155], v[224:227], v[104:107], v[152:155]
	v_mfma_f32_16x16x32_bf16 v[152:155], v[228:231], v[108:111], v[152:155]
	s_waitcnt lgkmcnt(0)
	s_cmp_eq_u32 s14, 0
	s_cbranch_scc1 .Lsc5_noy2_3
	v_mfma_f32_16x16x32_bf16 v[156:159], v[232:235], v[96:99], 0
	v_mfma_f32_16x16x32_bf16 v[156:159], v[236:239], v[100:103], v[156:159]
	v_mfma_f32_16x16x32_bf16 v[156:159], v[240:243], v[104:107], v[156:159]
	v_mfma_f32_16x16x32_bf16 v[156:159], v[244:247], v[108:111], v[156:159]

.Lsc5_noy3_3:
	ds_write_b64 v84, v[160:161]
	ds_write_b64 v84, v[162:163] offset:1024
	s_waitcnt lgkmcnt(0)
	s_barrier
	ds_read_b32 v50, v79 offset:1024
	ds_read_b32 v51, v79 offset:1088
	ds_read_b64_tr_b16 v[128:129], v73 offset:34816
	ds_read_b64_tr_b16 v[130:131], v73 offset:35968
	ds_read_b64_tr_b16 v[132:133], v73 offset:37120
	ds_read_b64_tr_b16 v[134:135], v73 offset:38272
	ds_read_b64_tr_b16 v[136:137], v76 offset:17408
	ds_read_b64_tr_b16 v[138:139], v76 offset:21760
	ds_read_b64_tr_b16 v[140:141], v76 offset:17440
	ds_read_b64_tr_b16 v[142:143], v76 offset:21792
	ds_read_b64_tr_b16 v[144:145], v76 offset:26112
	ds_read_b64_tr_b16 v[146:147], v76 offset:30464
	ds_read_b64_tr_b16 v[148:149], v76 offset:26144
	ds_read_b64_tr_b16 v[150:151], v76 offset:30496
	s_add_u32 s3, s34, 8
	s_min_u32 s3, s3, 67
	s_cmp_lt_u32 s3, 4
	s_cselect_b32 s4, s16, s17
	s_mul_i32 s5, s3, s15
	s_add_i32 s4, s4, s5
	s_lshl_b32 s5, s4, 16
	s_lshl_b32 s4, s4, 11
	s_add_u32 s40, s18, s5
	s_addc_u32 s41, s19, 0
	s_add_u32 s42, s20, s5
	s_addc_u32 s43, s21, 0
	s_add_u32 s44, s22, s5
	s_addc_u32 s45, s23, 0
	s_add_u32 s46, s24, s4
	s_addc_u32 s47, s25, 0
	s_add_u32 s50, s26, s4
	s_addc_u32 s51, s27, 0
	global_load_dwordx4 v[180:183], v53, s[40:41]
	global_load_dwordx4 v[184:187], v54, s[40:41]
	global_load_dwordx4 v[188:191], v53, s[42:43]
	global_load_dwordx4 v[192:195], v54, s[42:43]
	global_load_dwordx2 v[196:197], v55, s[44:45]
	global_load_dword v198, v56, s[46:47]
	global_load_dword v199, v56, s[50:51]
	s_waitcnt lgkmcnt(6)
	v_mfma_f32_16x16x32_bf16 v[42:45], v[128:131], v[136:139], v[42:45]
	ds_read_b64_tr_b16 v[112:113], v82 offset:0
	ds_read_b64_tr_b16 v[114:115], v82 offset:288
	ds_read_b64_tr_b16 v[116:117], v82 offset:2304
	ds_read_b64_tr_b16 v[118:119], v82 offset:2592
	s_waitcnt lgkmcnt(8)
	v_mfma_f32_16x16x32_bf16 v[46:49], v[128:131], v[140:143], v[46:49]
	ds_read_b64_tr_b16 v[120:121], v82 offset:4608
	ds_read_b64_tr_b16 v[122:123], v82 offset:4896
	ds_read_b64_tr_b16 v[124:125], v82 offset:6912
	ds_read_b64_tr_b16 v[126:127], v82 offset:7200
	s_waitcnt lgkmcnt(10)
	v_mfma_f32_16x16x32_bf16 v[42:45], v[132:135], v[144:147], v[42:45]
	ds_read_b128 v[164:167], v86
	ds_read_b128 v[168:171], v86 offset:1024
	s_waitcnt lgkmcnt(10)
	v_mfma_f32_16x16x32_bf16 v[46:49], v[132:135], v[148:151], v[46:49]
	s_waitcnt vmcnt(16)
	ds_write_b128 v60, v[2:5] offset:0
	ds_write_b128 v60, v[6:9] offset:8704
	s_waitcnt lgkmcnt(10)
	v_mfma_f32_16x16x32_bf16 v[172:175], v[112:115], v[96:99], 0
	ds_write_b128 v60, v[10:13] offset:17408
	ds_write_b128 v60, v[14:17] offset:26112
	s_waitcnt lgkmcnt(10)
	v_mfma_f32_16x16x32_bf16 v[172:175], v[116:119], v[100:103], v[172:175]
	ds_write_b64 v63, v[18:19] offset:34816
	v_add_f32_e32 v92, v20, v52
	v_mul_f32_e32 v92, 0x3fb8aa3b, v92
	v_exp_f32_e32 v92, v92
	v_mov_b32_e32 v52, v21
	ds_write_b32 v78, v92 offset:0
	s_waitcnt lgkmcnt(10)
	v_mfma_f32_16x16x32_bf16 v[172:175], v[120:123], v[104:107], v[172:175]
	ds_read_b128 v[200:203], v68 offset:0
	ds_read_b128 v[204:207], v68 offset:64
	s_waitcnt lgkmcnt(10)
	v_mfma_f32_16x16x32_bf16 v[172:175], v[124:127], v[108:111], v[172:175]
	ds_read_b128 v[208:211], v68 offset:128
	ds_read_b128 v[212:215], v68 offset:192
	s_waitcnt lgkmcnt(11)
	v_mfma_f32_16x16x32_bf16 v[172:175], v[128:131], v[164:167], v[172:175]
	ds_read_b128 v[216:219], v71 offset:17408
	ds_read_b128 v[220:223], v71 offset:17472
	ds_read_b128 v[224:227], v71 offset:17536
	ds_read_b128 v[228:231], v71 offset:17600
	s_waitcnt lgkmcnt(14)
	s_cmp_eq_u32 s11, 0
	s_cbranch_scc1 .Lsc5_nopv1_4
	v_mfma_f32_16x16x32_bf16 v[172:175], v[132:135], v[168:171], v[172:175]

.Lsc5_noy_4:
	v_mul_f32_e32 v42, v42, v50
	v_mul_f32_e32 v43, v43, v50
	v_mul_f32_e32 v44, v44, v50
	v_mul_f32_e32 v45, v45, v50
	v_mul_f32_e32 v46, v46, v51
	v_mul_f32_e32 v47, v47, v51
	v_mul_f32_e32 v48, v48, v51
	v_mul_f32_e32 v49, v49, v51
	v_cvt_pk_bf16_f32 v88, v42, v43
	v_cvt_pk_bf16_f32 v89, v44, v45
	v_cvt_pk_bf16_f32 v90, v46, v47
	v_cvt_pk_bf16_f32 v91, v48, v49
	ds_write_b64 v81, v[88:89]
	ds_write_b64 v81, v[90:91] offset:1152
	s_add_u32 s3, s34, 4
	s_cmp_lt_u32 s3, 4
	s_cselect_b32 s4, s16, s17
	s_mul_i32 s5, s3, s15
	s_add_i32 s4, s4, s5
	s_lshl_b32 s4, s4, 16
	s_add_u32 s64, s28, s4
	s_addc_u32 s65, s29, 0
	v_cvt_pk_bf16_f32 v176, v172, v173
	v_cvt_pk_bf16_f32 v177, v174, v175
	s_waitcnt lgkmcnt(2)
	v_mfma_f32_16x16x32_bf16 v[152:155], v[216:219], v[200:203], 0
	v_mfma_f32_16x16x32_bf16 v[152:155], v[220:223], v[204:207], v[152:155]
	v_mfma_f32_16x16x32_bf16 v[152:155], v[224:227], v[208:211], v[152:155]
	v_mfma_f32_16x16x32_bf16 v[152:155], v[228:231], v[212:215], v[152:155]
	s_waitcnt lgkmcnt(0)
	s_cmp_eq_u32 s14, 0
	s_cbranch_scc1 .Lsc5_noy2_4
	v_mfma_f32_16x16x32_bf16 v[156:159], v[232:235], v[200:203], 0
	v_mfma_f32_16x16x32_bf16 v[156:159], v[236:239], v[204:207], v[156:159]
	v_mfma_f32_16x16x32_bf16 v[156:159], v[240:243], v[208:211], v[156:159]
	v_mfma_f32_16x16x32_bf16 v[156:159], v[244:247], v[212:215], v[156:159]

.Lsc5_noy3_4:
	ds_write_b64 v85, v[160:161]
	ds_write_b64 v85, v[162:163] offset:1024
	s_waitcnt lgkmcnt(0)
	s_barrier
	ds_read_b32 v50, v79 offset:0
	ds_read_b32 v51, v79 offset:64
	ds_read_b64_tr_b16 v[128:129], v74 offset:34816
	ds_read_b64_tr_b16 v[130:131], v74 offset:35968
	ds_read_b64_tr_b16 v[132:133], v74 offset:37120
	ds_read_b64_tr_b16 v[134:135], v74 offset:38272
	ds_read_b64_tr_b16 v[136:137], v77 offset:17408
	ds_read_b64_tr_b16 v[138:139], v77 offset:21760
	ds_read_b64_tr_b16 v[140:141], v77 offset:17440
	ds_read_b64_tr_b16 v[142:143], v77 offset:21792
	ds_read_b64_tr_b16 v[144:145], v77 offset:26112
	ds_read_b64_tr_b16 v[146:147], v77 offset:30464
	ds_read_b64_tr_b16 v[148:149], v77 offset:26144
	ds_read_b64_tr_b16 v[150:151], v77 offset:30496
	s_add_u32 s3, s34, 9
	s_min_u32 s3, s3, 67
	s_cmp_lt_u32 s3, 4
	s_cselect_b32 s4, s16, s17
	s_mul_i32 s5, s3, s15
	s_add_i32 s4, s4, s5
	s_lshl_b32 s5, s4, 16
	s_lshl_b32 s4, s4, 11
	s_add_u32 s40, s18, s5
	s_addc_u32 s41, s19, 0
	s_add_u32 s42, s20, s5
	s_addc_u32 s43, s21, 0
	s_add_u32 s44, s22, s5
	s_addc_u32 s45, s23, 0
	s_add_u32 s46, s24, s4
	s_addc_u32 s47, s25, 0
	s_add_u32 s50, s26, s4
	s_addc_u32 s51, s27, 0
	global_load_dwordx4 v[2:5], v53, s[40:41]
	global_load_dwordx4 v[6:9], v54, s[40:41]
	global_load_dwordx4 v[10:13], v53, s[42:43]
	global_load_dwordx4 v[14:17], v54, s[42:43]
	global_load_dwordx2 v[18:19], v55, s[44:45]
	global_load_dword v20, v56, s[46:47]
	global_load_dword v21, v56, s[50:51]
	s_waitcnt lgkmcnt(6)
	v_mfma_f32_16x16x32_bf16 v[42:45], v[128:131], v[136:139], v[42:45]
	ds_read_b64_tr_b16 v[112:113], v83 offset:0
	ds_read_b64_tr_b16 v[114:115], v83 offset:288
	ds_read_b64_tr_b16 v[116:117], v83 offset:2304
	ds_read_b64_tr_b16 v[118:119], v83 offset:2592
	s_waitcnt lgkmcnt(8)
	v_mfma_f32_16x16x32_bf16 v[46:49], v[128:131], v[140:143], v[46:49]
	ds_read_b64_tr_b16 v[120:121], v83 offset:4608
	ds_read_b64_tr_b16 v[122:123], v83 offset:4896
	ds_read_b64_tr_b16 v[124:125], v83 offset:6912
	ds_read_b64_tr_b16 v[126:127], v83 offset:7200
	s_waitcnt lgkmcnt(10)
	v_mfma_f32_16x16x32_bf16 v[42:45], v[132:135], v[144:147], v[42:45]
	ds_read_b128 v[164:167], v87
	ds_read_b128 v[168:171], v87 offset:1024
	s_waitcnt lgkmcnt(10)
	v_mfma_f32_16x16x32_bf16 v[46:49], v[132:135], v[148:151], v[46:49]
	s_waitcnt vmcnt(16)
	ds_write_b128 v61, v[22:25] offset:0
	ds_write_b128 v61, v[26:29] offset:8704
	s_waitcnt lgkmcnt(10)
	v_mfma_f32_16x16x32_bf16 v[172:175], v[112:115], v[200:203], 0
	ds_write_b128 v61, v[30:33] offset:17408
	ds_write_b128 v61, v[34:37] offset:26112
	s_waitcnt lgkmcnt(10)
	v_mfma_f32_16x16x32_bf16 v[172:175], v[116:119], v[204:207], v[172:175]
	ds_write_b64 v64, v[38:39] offset:34816
	v_add_f32_e32 v92, v40, v52
	v_mul_f32_e32 v92, 0x3fb8aa3b, v92
	v_exp_f32_e32 v92, v92
	v_mov_b32_e32 v52, v41
	ds_write_b32 v78, v92 offset:512
	s_waitcnt lgkmcnt(10)
	v_mfma_f32_16x16x32_bf16 v[172:175], v[120:123], v[208:211], v[172:175]
	ds_read_b128 v[96:99], v66 offset:0
	ds_read_b128 v[100:103], v66 offset:64
	s_waitcnt lgkmcnt(10)
	v_mfma_f32_16x16x32_bf16 v[172:175], v[124:127], v[212:215], v[172:175]
	ds_read_b128 v[104:107], v66 offset:128
	ds_read_b128 v[108:111], v66 offset:192
	s_waitcnt lgkmcnt(11)
	v_mfma_f32_16x16x32_bf16 v[172:175], v[128:131], v[164:167], v[172:175]
	ds_read_b128 v[216:219], v69 offset:17408
	ds_read_b128 v[220:223], v69 offset:17472
	ds_read_b128 v[224:227], v69 offset:17536
	ds_read_b128 v[228:231], v69 offset:17600
	s_waitcnt lgkmcnt(14)
	s_cmp_eq_u32 s11, 0
	s_cbranch_scc1 .Lsc5_nopv1_5
	v_mfma_f32_16x16x32_bf16 v[172:175], v[132:135], v[168:171], v[172:175]

.Lsc5_noy_5:
	v_mul_f32_e32 v42, v42, v50
	v_mul_f32_e32 v43, v43, v50
	v_mul_f32_e32 v44, v44, v50
	v_mul_f32_e32 v45, v45, v50
	v_mul_f32_e32 v46, v46, v51
	v_mul_f32_e32 v47, v47, v51
	v_mul_f32_e32 v48, v48, v51
	v_mul_f32_e32 v49, v49, v51
	v_cvt_pk_bf16_f32 v88, v42, v43
	v_cvt_pk_bf16_f32 v89, v44, v45
	v_cvt_pk_bf16_f32 v90, v46, v47
	v_cvt_pk_bf16_f32 v91, v48, v49
	ds_write_b64 v80, v[88:89]
	ds_write_b64 v80, v[90:91] offset:1152
	s_add_u32 s3, s34, 5
	s_cmp_lt_u32 s3, 4
	s_cselect_b32 s4, s16, s17
	s_mul_i32 s5, s3, s15
	s_add_i32 s4, s4, s5
	s_lshl_b32 s4, s4, 16
	s_add_u32 s64, s28, s4
	s_addc_u32 s65, s29, 0
	v_cvt_pk_bf16_f32 v176, v172, v173
	v_cvt_pk_bf16_f32 v177, v174, v175
	s_waitcnt lgkmcnt(2)
	v_mfma_f32_16x16x32_bf16 v[152:155], v[216:219], v[96:99], 0
	v_mfma_f32_16x16x32_bf16 v[152:155], v[220:223], v[100:103], v[152:155]
	v_mfma_f32_16x16x32_bf16 v[152:155], v[224:227], v[104:107], v[152:155]
	v_mfma_f32_16x16x32_bf16 v[152:155], v[228:231], v[108:111], v[152:155]
	s_waitcnt lgkmcnt(0)
	s_cmp_eq_u32 s14, 0
	s_cbranch_scc1 .Lsc5_noy2_5
	v_mfma_f32_16x16x32_bf16 v[156:159], v[232:235], v[96:99], 0
	v_mfma_f32_16x16x32_bf16 v[156:159], v[236:239], v[100:103], v[156:159]
	v_mfma_f32_16x16x32_bf16 v[156:159], v[240:243], v[104:107], v[156:159]
	v_mfma_f32_16x16x32_bf16 v[156:159], v[244:247], v[108:111], v[156:159]

; #define SCAN_BAR() asm volatile("s_waitcnt lgkmcnt(0)\n\ts_barrier" ::: "memory")
; __device__ void scan_phase(LAS unsigned char* lds, const Params& p) {
;     ...
;         for (int n0 = 0; n0 < 68; n0 += 4) {
;             SCAN_STAGE(1, k4B, q4B, v4B, rvB, tlB); SCAN_LOAD(min(n0 + 5, 67), k4B, q4B, v4B, rvB, tlB); SCAN_MAT(0, n0); SCAN_BAR();
;             SCAN_STAGE(0, k4C, q4C, v4C, rvC, tlC); SCAN_LOAD(min(n0 + 6, 67), k4C, q4C, v4C, rvC, tlC); SCAN_MAT(1, n0 + 1); SCAN_BAR();
;             SCAN_STAGE(1, k4D, q4D, v4D, rvD, tlD); SCAN_LOAD(min(n0 + 7, 67), k4D, q4D, v4D, rvD, tlD); SCAN_MAT(0, n0 + 2); SCAN_BAR();
;             SCAN_STAGE(0, k4A, q4A, v4A, rvA, tlA); SCAN_LOAD(min(n0 + 8, 67), k4A, q4A, v4A, rvA, tlA); SCAN_MAT(1, n0 + 3); SCAN_BAR();
;         }
.Lsc5_noy3_5:
	ds_write_b64 v84, v[160:161]
	ds_write_b64 v84, v[162:163] offset:1024
	s_waitcnt lgkmcnt(0)
	s_barrier
	s_add_u32 s34, s34, 6
	s_cmp_lt_u32 s34, 66
	s_cbranch_scc1 .Lsc5_loop
	ds_read_b32 v50, v79 offset:512
	ds_read_b32 v51, v79 offset:576
	ds_read_b64_tr_b16 v[128:129], v72 offset:34816
	ds_read_b64_tr_b16 v[130:131], v72 offset:35968
	ds_read_b64_tr_b16 v[132:133], v72 offset:37120
	ds_read_b64_tr_b16 v[134:135], v72 offset:38272
	ds_read_b64_tr_b16 v[136:137], v75 offset:17408
	ds_read_b64_tr_b16 v[138:139], v75 offset:21760
	ds_read_b64_tr_b16 v[140:141], v75 offset:17440
	ds_read_b64_tr_b16 v[142:143], v75 offset:21792
	ds_read_b64_tr_b16 v[144:145], v75 offset:26112
	ds_read_b64_tr_b16 v[146:147], v75 offset:30464
	ds_read_b64_tr_b16 v[148:149], v75 offset:26144
	ds_read_b64_tr_b16 v[150:151], v75 offset:30496
	s_add_u32 s3, s34, 4
	s_min_u32 s3, s3, 67
	s_cmp_lt_u32 s3, 4
	s_cselect_b32 s4, s16, s17
	s_mul_i32 s5, s3, s15
	s_add_i32 s4, s4, s5
	s_lshl_b32 s5, s4, 16
	s_lshl_b32 s4, s4, 11
	s_add_u32 s40, s18, s5
	s_addc_u32 s41, s19, 0
	s_add_u32 s42, s20, s5
	s_addc_u32 s43, s21, 0
	s_add_u32 s44, s22, s5
	s_addc_u32 s45, s23, 0
	s_add_u32 s46, s24, s4
	s_addc_u32 s47, s25, 0
	s_add_u32 s50, s26, s4
	s_addc_u32 s51, s27, 0
	global_load_dwordx4 v[22:25], v53, s[40:41]
	global_load_dwordx4 v[26:29], v54, s[40:41]
	global_load_dwordx4 v[30:33], v53, s[42:43]
	global_load_dwordx4 v[34:37], v54, s[42:43]
	global_load_dwordx2 v[38:39], v55, s[44:45]
	global_load_dword v40, v56, s[46:47]
	global_load_dword v41, v56, s[50:51]
	s_waitcnt lgkmcnt(6)
	v_mfma_f32_16x16x32_bf16 v[42:45], v[128:131], v[136:139], v[42:45]
	ds_read_b64_tr_b16 v[112:113], v82 offset:0
	ds_read_b64_tr_b16 v[114:115], v82 offset:288
	ds_read_b64_tr_b16 v[116:117], v82 offset:2304
	ds_read_b64_tr_b16 v[118:119], v82 offset:2592
	s_waitcnt lgkmcnt(8)
	v_mfma_f32_16x16x32_bf16 v[46:49], v[128:131], v[140:143], v[46:49]
	ds_read_b64_tr_b16 v[120:121], v82 offset:4608
	ds_read_b64_tr_b16 v[122:123], v82 offset:4896
	ds_read_b64_tr_b16 v[124:125], v82 offset:6912
	ds_read_b64_tr_b16 v[126:127], v82 offset:7200
	s_waitcnt lgkmcnt(10)
	v_mfma_f32_16x16x32_bf16 v[42:45], v[132:135], v[144:147], v[42:45]
	ds_read_b128 v[164:167], v86
	ds_read_b128 v[168:171], v86 offset:1024
	s_waitcnt lgkmcnt(10)
	v_mfma_f32_16x16x32_bf16 v[46:49], v[132:135], v[148:151], v[46:49]
	s_waitcnt vmcnt(16)
	ds_write_b128 v62, v[180:183] offset:0
	ds_write_b128 v62, v[184:187] offset:8704
	s_waitcnt lgkmcnt(10)
	v_mfma_f32_16x16x32_bf16 v[172:175], v[112:115], v[96:99], 0
	ds_write_b128 v62, v[188:191] offset:17408
	ds_write_b128 v62, v[192:195] offset:26112
	s_waitcnt lgkmcnt(10)
	v_mfma_f32_16x16x32_bf16 v[172:175], v[116:119], v[100:103], v[172:175]
	ds_write_b64 v65, v[196:197] offset:34816
	v_add_f32_e32 v92, v198, v52
	v_mul_f32_e32 v92, 0x3fb8aa3b, v92
	v_exp_f32_e32 v92, v92
	v_mov_b32_e32 v52, v199
	ds_write_b32 v78, v92 offset:1024
	s_waitcnt lgkmcnt(10)
	v_mfma_f32_16x16x32_bf16 v[172:175], v[120:123], v[104:107], v[172:175]
	ds_read_b128 v[200:203], v67 offset:0
	ds_read_b128 v[204:207], v67 offset:64
	s_waitcnt lgkmcnt(10)
	v_mfma_f32_16x16x32_bf16 v[172:175], v[124:127], v[108:111], v[172:175]
	ds_read_b128 v[208:211], v67 offset:128
	ds_read_b128 v[212:215], v67 offset:192
	s_waitcnt lgkmcnt(11)
	v_mfma_f32_16x16x32_bf16 v[172:175], v[128:131], v[164:167], v[172:175]
	ds_read_b128 v[216:219], v70 offset:17408
	ds_read_b128 v[220:223], v70 offset:17472
	ds_read_b128 v[224:227], v70 offset:17536
	ds_read_b128 v[228:231], v70 offset:17600
	s_waitcnt lgkmcnt(14)
	s_cmp_eq_u32 s11, 0
	s_cbranch_scc1 .Lsc5_nopv1_t0
	v_mfma_f32_16x16x32_bf16 v[172:175], v[132:135], v[168:171], v[172:175]

.Lsc5_noy_t0:
	v_mul_f32_e32 v42, v42, v50
	v_mul_f32_e32 v43, v43, v50
	v_mul_f32_e32 v44, v44, v50
	v_mul_f32_e32 v45, v45, v50
	v_mul_f32_e32 v46, v46, v51
	v_mul_f32_e32 v47, v47, v51
	v_mul_f32_e32 v48, v48, v51
	v_mul_f32_e32 v49, v49, v51
	v_cvt_pk_bf16_f32 v88, v42, v43
	v_cvt_pk_bf16_f32 v89, v44, v45
	v_cvt_pk_bf16_f32 v90, v46, v47
	v_cvt_pk_bf16_f32 v91, v48, v49
	ds_write_b64 v81, v[88:89]
	ds_write_b64 v81, v[90:91] offset:1152
	s_add_u32 s3, s34, 0
	s_cmp_lt_u32 s3, 4
	s_cselect_b32 s4, s16, s17
	s_mul_i32 s5, s3, s15
	s_add_i32 s4, s4, s5
	s_lshl_b32 s4, s4, 16
	s_add_u32 s64, s28, s4
	s_addc_u32 s65, s29, 0
	v_cvt_pk_bf16_f32 v176, v172, v173
	v_cvt_pk_bf16_f32 v177, v174, v175
	s_waitcnt lgkmcnt(2)
	v_mfma_f32_16x16x32_bf16 v[152:155], v[216:219], v[200:203], 0
	v_mfma_f32_16x16x32_bf16 v[152:155], v[220:223], v[204:207], v[152:155]
	v_mfma_f32_16x16x32_bf16 v[152:155], v[224:227], v[208:211], v[152:155]
	v_mfma_f32_16x16x32_bf16 v[152:155], v[228:231], v[212:215], v[152:155]
	s_waitcnt lgkmcnt(0)
	s_cmp_eq_u32 s14, 0
	s_cbranch_scc1 .Lsc5_noy2_t0
	v_mfma_f32_16x16x32_bf16 v[156:159], v[232:235], v[200:203], 0
	v_mfma_f32_16x16x32_bf16 v[156:159], v[236:239], v[204:207], v[156:159]
	v_mfma_f32_16x16x32_bf16 v[156:159], v[240:243], v[208:211], v[156:159]
	v_mfma_f32_16x16x32_bf16 v[156:159], v[244:247], v[212:215], v[156:159]

.Lsc5_noy3_t0:
	ds_write_b64 v85, v[160:161]
	ds_write_b64 v85, v[162:163] offset:1024
	s_waitcnt lgkmcnt(0)
	s_barrier
	ds_read_b64_tr_b16 v[128:129], v73 offset:34816
	ds_read_b64_tr_b16 v[130:131], v73 offset:35968
	ds_read_b64_tr_b16 v[132:133], v73 offset:37120
	ds_read_b64_tr_b16 v[134:135], v73 offset:38272
	ds_read_b64_tr_b16 v[136:137], v76 offset:17408
	ds_read_b64_tr_b16 v[138:139], v76 offset:21760
	ds_read_b64_tr_b16 v[140:141], v76 offset:17440
	ds_read_b64_tr_b16 v[142:143], v76 offset:21792
	ds_read_b64_tr_b16 v[144:145], v76 offset:26112
	ds_read_b64_tr_b16 v[146:147], v76 offset:30464
	ds_read_b64_tr_b16 v[148:149], v76 offset:26144
	ds_read_b64_tr_b16 v[150:151], v76 offset:30496
	s_add_u32 s3, s34, 5
	s_min_u32 s3, s3, 67
	s_cmp_lt_u32 s3, 4
	s_cselect_b32 s4, s16, s17
	s_mul_i32 s5, s3, s15
	s_add_i32 s4, s4, s5
	s_lshl_b32 s5, s4, 16
	s_lshl_b32 s4, s4, 11
	s_add_u32 s40, s18, s5
	s_addc_u32 s41, s19, 0
	s_add_u32 s42, s20, s5
	s_addc_u32 s43, s21, 0
	s_add_u32 s44, s22, s5
	s_addc_u32 s45, s23, 0
	s_add_u32 s46, s24, s4
	s_addc_u32 s47, s25, 0
	s_add_u32 s50, s26, s4
	s_addc_u32 s51, s27, 0
	global_load_dwordx4 v[180:183], v53, s[40:41]
	global_load_dwordx4 v[184:187], v54, s[40:41]
	global_load_dwordx4 v[188:191], v53, s[42:43]
	global_load_dwordx4 v[192:195], v54, s[42:43]
	global_load_dwordx2 v[196:197], v55, s[44:45]
	global_load_dword v198, v56, s[46:47]
	global_load_dword v199, v56, s[50:51]
	s_waitcnt lgkmcnt(6)
	v_mfma_f32_16x16x32_bf16 v[42:45], v[128:131], v[136:139], v[42:45]
	ds_read_b64_tr_b16 v[112:113], v83 offset:0
	ds_read_b64_tr_b16 v[114:115], v83 offset:288
	ds_read_b64_tr_b16 v[116:117], v83 offset:2304
	ds_read_b64_tr_b16 v[118:119], v83 offset:2592
	s_waitcnt lgkmcnt(8)
	v_mfma_f32_16x16x32_bf16 v[46:49], v[128:131], v[140:143], v[46:49]
	ds_read_b64_tr_b16 v[120:121], v83 offset:4608
	ds_read_b64_tr_b16 v[122:123], v83 offset:4896
	ds_read_b64_tr_b16 v[124:125], v83 offset:6912
	ds_read_b64_tr_b16 v[126:127], v83 offset:7200
	s_waitcnt lgkmcnt(10)
	v_mfma_f32_16x16x32_bf16 v[42:45], v[132:135], v[144:147], v[42:45]
	ds_read_b128 v[164:167], v87
	ds_read_b128 v[168:171], v87 offset:1024
	s_waitcnt lgkmcnt(10)
	v_mfma_f32_16x16x32_bf16 v[46:49], v[132:135], v[148:151], v[46:49]
	s_waitcnt vmcnt(16)
	ds_write_b128 v60, v[2:5] offset:0
	ds_write_b128 v60, v[6:9] offset:8704
	s_waitcnt lgkmcnt(10)
	v_mfma_f32_16x16x32_bf16 v[172:175], v[112:115], v[200:203], 0
	ds_write_b128 v60, v[10:13] offset:17408
	ds_write_b128 v60, v[14:17] offset:26112
	s_waitcnt lgkmcnt(10)
	v_mfma_f32_16x16x32_bf16 v[172:175], v[116:119], v[204:207], v[172:175]
	ds_write_b64 v63, v[18:19] offset:34816
	v_add_f32_e32 v92, v20, v52
	v_mul_f32_e32 v92, 0x3fb8aa3b, v92
	v_exp_f32_e32 v92, v92
	v_mov_b32_e32 v52, v21
	ds_write_b32 v78, v92 offset:0
	s_waitcnt lgkmcnt(10)
	v_mfma_f32_16x16x32_bf16 v[172:175], v[120:123], v[208:211], v[172:175]
	s_waitcnt lgkmcnt(8)
	v_mfma_f32_16x16x32_bf16 v[172:175], v[124:127], v[212:215], v[172:175]
	s_waitcnt lgkmcnt(7)
	v_mfma_f32_16x16x32_bf16 v[172:175], v[128:131], v[164:167], v[172:175]
	s_waitcnt lgkmcnt(6)
	s_cmp_eq_u32 s11, 0
	s_cbranch_scc1 .Lsc5_nopv1_t1
	v_mfma_f32_16x16x32_bf16 v[172:175], v[132:135], v[168:171], v[172:175]
.Lsc5_nopv1_t1:
	s_add_u32 s3, s34, 1
	s_cmp_lt_u32 s3, 4
	s_cselect_b32 s4, s16, s17
	s_mul_i32 s5, s3, s15
	s_add_i32 s4, s4, s5
	s_lshl_b32 s4, s4, 16
	s_add_u32 s64, s28, s4
	s_addc_u32 s65, s29, 0
	s_nop 7
	v_cvt_pk_bf16_f32 v176, v172, v173
	v_cvt_pk_bf16_f32 v177, v174, v175
	global_store_dwordx2 v57, v[176:177], s[64:65]
	s_waitcnt lgkmcnt(0)
	s_barrier
	s_add_u32 s9, s9, s35
	s_cmp_lt_u32 s9, 0x100
	s_cbranch_scc1 .Lsc5_item
